# PROJ epilogue q/k-norm chunks: norm-gain loads issued at the top of the block (in flight during the sum-of-squares reduction)
# baseline (speedup 1.0000x reference)
.LBB0_617:
	global_load_dwordx4 v[220:223], v[132:133], off
	global_load_dwordx4 v[224:227], v[132:133], off offset:64
	global_load_dwordx4 v[228:231], v[132:133], off offset:128
	global_load_dwordx4 v[232:235], v[132:133], off offset:192
	v_pk_mul_f32 v[112:113], v[144:145], v[144:145]
	v_pk_mul_f32 v[114:115], v[120:121], v[120:121]
	v_add_f32_e32 v112, v112, v113
	v_add_f32_e32 v112, v114, v112
	v_pk_mul_f32 v[116:117], v[134:135], v[134:135]
	v_add_f32_e32 v112, v115, v112
	v_add_f32_e32 v112, v116, v112
	v_pk_mul_f32 v[118:119], v[124:125], v[124:125]
	v_add_f32_e32 v112, v117, v112
	v_add_f32_e32 v112, v118, v112
	v_pk_mul_f32 v[122:123], v[140:141], v[140:141]
	v_add_f32_e32 v112, v119, v112
	v_add_f32_e32 v112, v122, v112
	v_pk_mul_f32 v[142:143], v[138:139], v[138:139]
	v_add_f32_e32 v112, v123, v112
	v_add_f32_e32 v112, v142, v112
	v_pk_mul_f32 v[146:147], v[136:137], v[136:137]
	v_add_f32_e32 v112, v143, v112
	v_and_b32_e32 v114, 64, v200
	v_add_f32_e32 v112, v146, v112
	v_xor_b32_e32 v113, 16, v200
	v_add_u32_e32 v114, 64, v114
	v_pk_mul_f32 v[164:165], v[126:127], v[126:127]
	v_add_f32_e32 v112, v147, v112
	v_cmp_lt_i32_e32 vcc, v113, v114
	v_add_f32_e32 v112, v164, v112
	v_add_f32_e32 v112, v165, v112
	v_cndmask_b32_e32 v113, v200, v113, vcc
	v_lshlrev_b32_e32 v113, 2, v113
	ds_bpermute_b32 v113, v113, v112
	s_waitcnt lgkmcnt(0)
	v_add_f32_e32 v112, v112, v113
	v_xor_b32_e32 v113, 32, v200
	v_cmp_lt_i32_e32 vcc, v113, v114
	s_nop 1
	v_cndmask_b32_e32 v113, v200, v113, vcc
	v_lshlrev_b32_e32 v143, 2, v113
	ds_bpermute_b32 v113, v143, v112
	s_waitcnt lgkmcnt(0)
	v_add_f32_e32 v112, v112, v113
	v_fmamk_f32 v112, v112, 0x3c800000, v199
	v_cmp_gt_f32_e32 vcc, s73, v112
	v_mul_f32_e32 v113, 0x4b800000, v112
	s_nop 0
	v_cndmask_b32_e32 v112, v112, v113, vcc
	v_rsq_f32_e32 v112, v112
	s_nop 0
	v_mul_f32_e32 v113, 0x45800000, v112
	v_cndmask_b32_e32 v142, v112, v113, vcc
	s_waitcnt vmcnt(0)
	v_mov_b32_e32 v112, v220
	v_mov_b32_e32 v113, v221
	v_mov_b32_e32 v114, v222
	v_mov_b32_e32 v115, v223
	v_pk_mul_f32 v[112:113], v[112:113], v[142:143] op_sel_hi:[1,0]
	s_nop 0
	v_pk_mul_f32 v[144:145], v[144:145], v[112:113]
	v_pk_mul_f32 v[112:113], v[114:115], v[142:143] op_sel_hi:[1,0]
	s_nop 0
	v_pk_mul_f32 v[146:147], v[120:121], v[112:113]
	v_mov_b32_e32 v120, v224
	v_mov_b32_e32 v121, v225
	v_mov_b32_e32 v122, v226
	v_mov_b32_e32 v123, v227
	v_mov_b32_e32 v116, v228
	v_mov_b32_e32 v117, v229
	v_mov_b32_e32 v118, v230
	v_mov_b32_e32 v119, v231
	v_mov_b32_e32 v112, v232
	v_mov_b32_e32 v113, v233
	v_mov_b32_e32 v114, v234
	v_mov_b32_e32 v115, v235
	s_and_saveexec_b64 s[36:37], s[22:23]
	s_cbranch_execz .LBB0_619
	v_readlane_b32 vcc_lo, v253, 51
	v_lshlrev_b32_e32 v164, 6, v163
	v_mov_b32_e32 v165, v153
	v_readlane_b32 vcc_hi, v253, 52
	v_lshlrev_b32_e32 v166, 2, v161
	v_mov_b32_e32 v167, v153
	v_lshl_add_u64 v[164:165], vcc, 0, v[164:165]
	v_lshl_add_u64 v[168:169], v[164:165], 0, v[166:167]
	global_load_dwordx4 v[164:167], v[168:169], off
	s_nop 0
	global_load_dwordx4 v[168:171], v[168:169], off offset:32
	ds_bpermute_b32 v172, v143, v144
	ds_bpermute_b32 v173, v143, v145
	s_waitcnt vmcnt(0) lgkmcnt(0)
	v_pk_mul_f32 v[168:169], v[168:169], v[172:173]
	s_nop 0
	v_cndmask_b32_e64 v169, v169, -v169, s[4:5]
	v_cndmask_b32_e64 v168, v168, -v168, s[4:5]
	v_pk_fma_f32 v[144:145], v[144:145], v[164:165], v[168:169]
	ds_bpermute_b32 v164, v143, v146
	ds_bpermute_b32 v165, v143, v147
	s_waitcnt lgkmcnt(0)
	v_pk_mul_f32 v[164:165], v[170:171], v[164:165]
	s_nop 0
	v_cndmask_b32_e64 v165, v165, -v165, s[4:5]
	v_cndmask_b32_e64 v164, v164, -v164, s[4:5]
	v_pk_fma_f32 v[146:147], v[146:147], v[166:167], v[164:165]

.LBB0_629:
	global_load_dwordx4 v[220:223], v[132:133], off
	global_load_dwordx4 v[224:227], v[132:133], off offset:64
	global_load_dwordx4 v[228:231], v[132:133], off offset:128
	global_load_dwordx4 v[232:235], v[132:133], off offset:192
	v_pk_mul_f32 v[96:97], v[126:127], v[126:127]
	v_pk_mul_f32 v[98:99], v[122:123], v[122:123]
	v_add_f32_e32 v96, v96, v97
	v_add_f32_e32 v96, v98, v96
	v_pk_mul_f32 v[100:101], v[110:111], v[110:111]
	v_add_f32_e32 v96, v99, v96
	v_add_f32_e32 v96, v100, v96
	v_pk_mul_f32 v[102:103], v[108:109], v[108:109]
	v_add_f32_e32 v96, v101, v96
	v_add_f32_e32 v96, v102, v96
	v_pk_mul_f32 v[104:105], v[120:121], v[120:121]
	v_add_f32_e32 v96, v103, v96
	v_add_f32_e32 v96, v104, v96
	v_pk_mul_f32 v[106:107], v[118:119], v[118:119]
	v_add_f32_e32 v96, v105, v96
	v_add_f32_e32 v96, v106, v96
	v_pk_mul_f32 v[124:125], v[116:117], v[116:117]
	v_add_f32_e32 v96, v107, v96
	v_and_b32_e32 v98, 64, v200
	v_add_f32_e32 v96, v124, v96
	v_xor_b32_e32 v97, 16, v200
	v_add_u32_e32 v98, 64, v98
	v_pk_mul_f32 v[138:139], v[114:115], v[114:115]
	v_add_f32_e32 v96, v125, v96
	v_cmp_lt_i32_e32 vcc, v97, v98
	v_add_f32_e32 v96, v138, v96
	v_add_f32_e32 v96, v139, v96
	v_cndmask_b32_e32 v97, v200, v97, vcc
	v_lshlrev_b32_e32 v97, 2, v97
	ds_bpermute_b32 v97, v97, v96
	s_waitcnt lgkmcnt(0)
	v_add_f32_e32 v96, v96, v97
	v_xor_b32_e32 v97, 32, v200
	v_cmp_lt_i32_e32 vcc, v97, v98
	s_nop 1
	v_cndmask_b32_e32 v97, v200, v97, vcc
	v_lshlrev_b32_e32 v125, 2, v97
	ds_bpermute_b32 v97, v125, v96
	s_waitcnt lgkmcnt(0)
	v_add_f32_e32 v96, v96, v97
	v_fmamk_f32 v96, v96, 0x3c800000, v199
	v_cmp_gt_f32_e32 vcc, s73, v96
	v_mul_f32_e32 v97, 0x4b800000, v96
	s_nop 0
	v_cndmask_b32_e32 v96, v96, v97, vcc
	v_rsq_f32_e32 v96, v96
	s_nop 0
	v_mul_f32_e32 v97, 0x45800000, v96
	v_cndmask_b32_e32 v124, v96, v97, vcc
	s_waitcnt vmcnt(0)
	v_mov_b32_e32 v96, v220
	v_mov_b32_e32 v97, v221
	v_mov_b32_e32 v98, v222
	v_mov_b32_e32 v99, v223
	v_pk_mul_f32 v[96:97], v[96:97], v[124:125] op_sel_hi:[1,0]
	s_nop 0
	v_pk_mul_f32 v[126:127], v[126:127], v[96:97]
	v_pk_mul_f32 v[96:97], v[98:99], v[124:125] op_sel_hi:[1,0]
	s_nop 0
	v_pk_mul_f32 v[122:123], v[122:123], v[96:97]
	v_mov_b32_e32 v104, v224
	v_mov_b32_e32 v105, v225
	v_mov_b32_e32 v106, v226
	v_mov_b32_e32 v107, v227
	v_mov_b32_e32 v100, v228
	v_mov_b32_e32 v101, v229
	v_mov_b32_e32 v102, v230
	v_mov_b32_e32 v103, v231
	v_mov_b32_e32 v96, v232
	v_mov_b32_e32 v97, v233
	v_mov_b32_e32 v98, v234
	v_mov_b32_e32 v99, v235
	s_and_saveexec_b64 s[36:37], s[22:23]
	s_cbranch_execz .LBB0_631
	v_readlane_b32 vcc_lo, v253, 51
	v_lshlrev_b32_e32 v138, 6, v134
	v_mov_b32_e32 v139, v153
	v_readlane_b32 vcc_hi, v253, 52
	v_lshlrev_b32_e32 v140, 2, v161
	v_mov_b32_e32 v141, v153
	v_lshl_add_u64 v[138:139], vcc, 0, v[138:139]
	v_lshl_add_u64 v[142:143], v[138:139], 0, v[140:141]
	global_load_dwordx4 v[138:141], v[142:143], off
	s_nop 0
	global_load_dwordx4 v[142:145], v[142:143], off offset:32
	ds_bpermute_b32 v146, v125, v126
	ds_bpermute_b32 v147, v125, v127
	s_waitcnt vmcnt(0) lgkmcnt(0)
	v_pk_mul_f32 v[142:143], v[142:143], v[146:147]
	s_nop 0
	v_cndmask_b32_e64 v143, v143, -v143, s[4:5]
	v_cndmask_b32_e64 v142, v142, -v142, s[4:5]
	v_pk_fma_f32 v[126:127], v[126:127], v[138:139], v[142:143]
	ds_bpermute_b32 v138, v125, v122
	ds_bpermute_b32 v139, v125, v123
	s_waitcnt lgkmcnt(0)
	v_pk_mul_f32 v[138:139], v[144:145], v[138:139]
	s_nop 0
	v_cndmask_b32_e64 v139, v139, -v139, s[4:5]
	v_cndmask_b32_e64 v138, v138, -v138, s[4:5]
	v_pk_fma_f32 v[122:123], v[122:123], v[140:141], v[138:139]

.LBB0_641:
	global_load_dwordx4 v[220:223], v[132:133], off
	global_load_dwordx4 v[224:227], v[132:133], off offset:64
	global_load_dwordx4 v[228:231], v[132:133], off offset:128
	global_load_dwordx4 v[232:235], v[132:133], off offset:192
	v_pk_mul_f32 v[80:81], v[108:109], v[108:109]
	v_pk_mul_f32 v[82:83], v[104:105], v[104:105]
	v_add_f32_e32 v80, v80, v81
	v_add_f32_e32 v80, v82, v80
	v_pk_mul_f32 v[84:85], v[94:95], v[94:95]
	v_add_f32_e32 v80, v83, v80
	v_add_f32_e32 v80, v84, v80
	v_pk_mul_f32 v[86:87], v[92:93], v[92:93]
	v_add_f32_e32 v80, v85, v80
	v_add_f32_e32 v80, v86, v80
	v_pk_mul_f32 v[88:89], v[102:103], v[102:103]
	v_add_f32_e32 v80, v87, v80
	v_add_f32_e32 v80, v88, v80
	v_pk_mul_f32 v[90:91], v[100:101], v[100:101]
	v_add_f32_e32 v80, v89, v80
	v_add_f32_e32 v80, v90, v80
	v_pk_mul_f32 v[106:107], v[98:99], v[98:99]
	v_add_f32_e32 v80, v91, v80
	v_and_b32_e32 v82, 64, v200
	v_add_f32_e32 v80, v106, v80
	v_xor_b32_e32 v81, 16, v200
	v_add_u32_e32 v82, 64, v82
	v_pk_mul_f32 v[114:115], v[96:97], v[96:97]
	v_add_f32_e32 v80, v107, v80
	v_cmp_lt_i32_e32 vcc, v81, v82
	v_add_f32_e32 v80, v114, v80
	v_add_f32_e32 v80, v115, v80
	v_cndmask_b32_e32 v81, v200, v81, vcc
	v_lshlrev_b32_e32 v81, 2, v81
	ds_bpermute_b32 v81, v81, v80
	s_waitcnt lgkmcnt(0)
	v_add_f32_e32 v80, v80, v81
	v_xor_b32_e32 v81, 32, v200
	v_cmp_lt_i32_e32 vcc, v81, v82
	s_nop 1
	v_cndmask_b32_e32 v81, v200, v81, vcc
	v_lshlrev_b32_e32 v107, 2, v81
	ds_bpermute_b32 v81, v107, v80
	s_waitcnt lgkmcnt(0)
	v_add_f32_e32 v80, v80, v81
	v_fmamk_f32 v80, v80, 0x3c800000, v199
	v_cmp_gt_f32_e32 vcc, s73, v80
	v_mul_f32_e32 v81, 0x4b800000, v80
	s_nop 0
	v_cndmask_b32_e32 v80, v80, v81, vcc
	v_rsq_f32_e32 v80, v80
	s_nop 0
	v_mul_f32_e32 v81, 0x45800000, v80
	v_cndmask_b32_e32 v106, v80, v81, vcc
	s_waitcnt vmcnt(0)
	v_mov_b32_e32 v80, v220
	v_mov_b32_e32 v81, v221
	v_mov_b32_e32 v82, v222
	v_mov_b32_e32 v83, v223
	v_pk_mul_f32 v[80:81], v[80:81], v[106:107] op_sel_hi:[1,0]
	s_nop 0
	v_pk_mul_f32 v[108:109], v[108:109], v[80:81]
	v_pk_mul_f32 v[80:81], v[82:83], v[106:107] op_sel_hi:[1,0]
	s_nop 0
	v_pk_mul_f32 v[104:105], v[104:105], v[80:81]
	v_mov_b32_e32 v88, v224
	v_mov_b32_e32 v89, v225
	v_mov_b32_e32 v90, v226
	v_mov_b32_e32 v91, v227
	v_mov_b32_e32 v84, v228
	v_mov_b32_e32 v85, v229
	v_mov_b32_e32 v86, v230
	v_mov_b32_e32 v87, v231
	v_mov_b32_e32 v80, v232
	v_mov_b32_e32 v81, v233
	v_mov_b32_e32 v82, v234
	v_mov_b32_e32 v83, v235
	s_and_saveexec_b64 s[36:37], s[22:23]
	s_cbranch_execz .LBB0_643
	v_readlane_b32 vcc_lo, v253, 51
	v_lshlrev_b32_e32 v114, 6, v111
	v_mov_b32_e32 v115, v153
	v_readlane_b32 vcc_hi, v253, 52
	v_lshlrev_b32_e32 v116, 2, v161
	v_mov_b32_e32 v117, v153
	v_lshl_add_u64 v[114:115], vcc, 0, v[114:115]
	v_lshl_add_u64 v[118:119], v[114:115], 0, v[116:117]
	global_load_dwordx4 v[114:117], v[118:119], off
	s_nop 0
	global_load_dwordx4 v[118:121], v[118:119], off offset:32
	ds_bpermute_b32 v122, v107, v108
	ds_bpermute_b32 v123, v107, v109
	s_waitcnt vmcnt(0) lgkmcnt(0)
	v_pk_mul_f32 v[118:119], v[118:119], v[122:123]
	s_nop 0
	v_cndmask_b32_e64 v119, v119, -v119, s[4:5]
	v_cndmask_b32_e64 v118, v118, -v118, s[4:5]
	v_pk_fma_f32 v[108:109], v[108:109], v[114:115], v[118:119]
	ds_bpermute_b32 v114, v107, v104
	ds_bpermute_b32 v115, v107, v105
	s_waitcnt lgkmcnt(0)
	v_pk_mul_f32 v[114:115], v[120:121], v[114:115]
	s_nop 0
	v_cndmask_b32_e64 v115, v115, -v115, s[4:5]
	v_cndmask_b32_e64 v114, v114, -v114, s[4:5]
	v_pk_fma_f32 v[104:105], v[104:105], v[116:117], v[114:115]

.LBB0_653:
	global_load_dwordx4 v[220:223], v[132:133], off
	global_load_dwordx4 v[224:227], v[132:133], off offset:64
	global_load_dwordx4 v[228:231], v[132:133], off offset:128
	global_load_dwordx4 v[232:235], v[132:133], off offset:192
	v_pk_mul_f32 v[64:65], v[92:93], v[92:93]
	v_pk_mul_f32 v[66:67], v[88:89], v[88:89]
	v_add_f32_e32 v64, v64, v65
	v_add_f32_e32 v64, v66, v64
	v_pk_mul_f32 v[68:69], v[78:79], v[78:79]
	v_add_f32_e32 v64, v67, v64
	v_add_f32_e32 v64, v68, v64
	v_pk_mul_f32 v[70:71], v[76:77], v[76:77]
	v_add_f32_e32 v64, v69, v64
	v_add_f32_e32 v64, v70, v64
	v_pk_mul_f32 v[72:73], v[86:87], v[86:87]
	v_add_f32_e32 v64, v71, v64
	v_add_f32_e32 v64, v72, v64
	v_pk_mul_f32 v[74:75], v[84:85], v[84:85]
	v_add_f32_e32 v64, v73, v64
	v_add_f32_e32 v64, v74, v64
	v_pk_mul_f32 v[90:91], v[82:83], v[82:83]
	v_add_f32_e32 v64, v75, v64
	v_and_b32_e32 v66, 64, v200
	v_add_f32_e32 v64, v90, v64
	v_xor_b32_e32 v65, 16, v200
	v_add_u32_e32 v66, 64, v66
	v_pk_mul_f32 v[96:97], v[80:81], v[80:81]
	v_add_f32_e32 v64, v91, v64
	v_cmp_lt_i32_e32 vcc, v65, v66
	v_add_f32_e32 v64, v96, v64
	v_add_f32_e32 v64, v97, v64
	v_cndmask_b32_e32 v65, v200, v65, vcc
	v_lshlrev_b32_e32 v65, 2, v65
	ds_bpermute_b32 v65, v65, v64
	s_waitcnt lgkmcnt(0)
	v_add_f32_e32 v64, v64, v65
	v_xor_b32_e32 v65, 32, v200
	v_cmp_lt_i32_e32 vcc, v65, v66
	s_nop 1
	v_cndmask_b32_e32 v65, v200, v65, vcc
	v_lshlrev_b32_e32 v91, 2, v65
	ds_bpermute_b32 v65, v91, v64
	s_waitcnt lgkmcnt(0)
	v_add_f32_e32 v64, v64, v65
	v_fmamk_f32 v64, v64, 0x3c800000, v199
	v_cmp_gt_f32_e32 vcc, s73, v64
	v_mul_f32_e32 v65, 0x4b800000, v64
	s_nop 0
	v_cndmask_b32_e32 v64, v64, v65, vcc
	v_rsq_f32_e32 v64, v64
	s_nop 0
	v_mul_f32_e32 v65, 0x45800000, v64
	v_cndmask_b32_e32 v90, v64, v65, vcc
	s_waitcnt vmcnt(0)
	v_mov_b32_e32 v64, v220
	v_mov_b32_e32 v65, v221
	v_mov_b32_e32 v66, v222
	v_mov_b32_e32 v67, v223
	v_pk_mul_f32 v[64:65], v[64:65], v[90:91] op_sel_hi:[1,0]
	s_nop 0
	v_pk_mul_f32 v[92:93], v[92:93], v[64:65]
	v_pk_mul_f32 v[64:65], v[66:67], v[90:91] op_sel_hi:[1,0]
	s_nop 0
	v_pk_mul_f32 v[88:89], v[88:89], v[64:65]
	v_mov_b32_e32 v72, v224
	v_mov_b32_e32 v73, v225
	v_mov_b32_e32 v74, v226
	v_mov_b32_e32 v75, v227
	v_mov_b32_e32 v68, v228
	v_mov_b32_e32 v69, v229
	v_mov_b32_e32 v70, v230
	v_mov_b32_e32 v71, v231
	v_mov_b32_e32 v64, v232
	v_mov_b32_e32 v65, v233
	v_mov_b32_e32 v66, v234
	v_mov_b32_e32 v67, v235
	s_and_saveexec_b64 s[26:27], s[22:23]
	s_cbranch_execz .LBB0_655
	v_readlane_b32 s22, v253, 51
	v_lshlrev_b32_e32 v152, 6, v95
	v_readlane_b32 s23, v253, 52
	ds_bpermute_b32 v104, v91, v92
	ds_bpermute_b32 v105, v91, v93
	v_lshl_add_u64 v[96:97], s[22:23], 0, v[152:153]
	v_lshlrev_b32_e32 v152, 2, v161
	v_lshl_add_u64 v[100:101], v[96:97], 0, v[152:153]
	global_load_dwordx4 v[96:99], v[100:101], off
	s_nop 0
	global_load_dwordx4 v[100:103], v[100:101], off offset:32
	s_waitcnt vmcnt(0) lgkmcnt(0)
	v_pk_mul_f32 v[100:101], v[100:101], v[104:105]
	s_nop 0
	v_cndmask_b32_e64 v101, v101, -v101, s[4:5]
	v_cndmask_b32_e64 v100, v100, -v100, s[4:5]
	v_pk_fma_f32 v[92:93], v[92:93], v[96:97], v[100:101]
	ds_bpermute_b32 v96, v91, v88
	ds_bpermute_b32 v97, v91, v89
	s_waitcnt lgkmcnt(0)
	v_pk_mul_f32 v[96:97], v[102:103], v[96:97]
	s_nop 0
	v_cndmask_b32_e64 v97, v97, -v97, s[4:5]
	v_cndmask_b32_e64 v96, v96, -v96, s[4:5]
	v_pk_fma_f32 v[88:89], v[88:89], v[98:99], v[96:97]

.LBB0_670:
	v_lshrrev_b32_e32 v86, 2, v129
	v_and_b32_e32 v87, 12, v86
	v_lshlrev_b32_e32 v152, 2, v87
	v_lshl_add_u64 v[66:67], v[66:67], 0, v[152:153]
	v_and_b32_e32 v65, 4, v86
	v_cmp_gt_u32_e64 s[4:5], 32, v129
	v_and_b32_e32 v88, 0xfcf, v83
	v_pk_mul_f32 v[80:81], v[52:53], v[82:83] op_sel_hi:[1,0]
	v_pk_mul_f32 v[78:79], v[54:55], v[82:83] op_sel_hi:[1,0]
	v_pk_mul_f32 v[76:77], v[56:57], v[82:83] op_sel_hi:[1,0]
	v_pk_mul_f32 v[74:75], v[58:59], v[82:83] op_sel_hi:[1,0]
	v_pk_mul_f32 v[72:73], v[60:61], v[82:83] op_sel_hi:[1,0]
	v_pk_mul_f32 v[70:71], v[62:63], v[82:83] op_sel_hi:[1,0]
	v_pk_mul_f32 v[68:69], v[48:49], v[82:83] op_sel_hi:[1,0]
	v_pk_mul_f32 v[62:63], v[50:51], v[82:83] op_sel_hi:[1,0]
	s_and_saveexec_b64 s[28:29], s[24:25]
	s_cbranch_execz .LBB0_674
	global_load_dwordx4 v[220:223], v[66:67], off
	global_load_dwordx4 v[224:227], v[66:67], off offset:64
	global_load_dwordx4 v[228:231], v[66:67], off offset:128
	global_load_dwordx4 v[232:235], v[66:67], off offset:192
	v_pk_mul_f32 v[48:49], v[80:81], v[80:81]
	v_pk_mul_f32 v[50:51], v[78:79], v[78:79]
	v_add_f32_e32 v48, v48, v49
	v_add_f32_e32 v48, v50, v48
	v_pk_mul_f32 v[52:53], v[76:77], v[76:77]
	v_add_f32_e32 v48, v51, v48
	v_add_f32_e32 v48, v52, v48
	v_pk_mul_f32 v[54:55], v[74:75], v[74:75]
	v_add_f32_e32 v48, v53, v48
	v_add_f32_e32 v48, v54, v48
	v_pk_mul_f32 v[56:57], v[72:73], v[72:73]
	v_add_f32_e32 v48, v55, v48
	v_add_f32_e32 v48, v56, v48
	v_pk_mul_f32 v[58:59], v[70:71], v[70:71]
	v_add_f32_e32 v48, v57, v48
	v_add_f32_e32 v48, v58, v48
	v_pk_mul_f32 v[60:61], v[68:69], v[68:69]
	v_add_f32_e32 v48, v59, v48
	v_and_b32_e32 v50, 64, v200
	v_add_f32_e32 v48, v60, v48
	v_xor_b32_e32 v49, 16, v200
	v_add_u32_e32 v50, 64, v50
	v_pk_mul_f32 v[90:91], v[62:63], v[62:63]
	v_add_f32_e32 v48, v61, v48
	v_cmp_lt_i32_e32 vcc, v49, v50
	v_add_f32_e32 v48, v90, v48
	v_add_f32_e32 v48, v91, v48
	v_cndmask_b32_e32 v49, v200, v49, vcc
	v_lshlrev_b32_e32 v49, 2, v49
	ds_bpermute_b32 v49, v49, v48
	s_waitcnt lgkmcnt(0)
	v_add_f32_e32 v48, v48, v49
	v_xor_b32_e32 v49, 32, v200
	v_cmp_lt_i32_e32 vcc, v49, v50
	s_nop 1
	v_cndmask_b32_e32 v49, v200, v49, vcc
	v_lshlrev_b32_e32 v61, 2, v49
	ds_bpermute_b32 v49, v61, v48
	s_waitcnt lgkmcnt(0)
	v_add_f32_e32 v48, v48, v49
	v_fmamk_f32 v48, v48, 0x3c800000, v199
	v_cmp_gt_f32_e32 vcc, s73, v48
	v_mul_f32_e32 v49, 0x4b800000, v48
	s_nop 0
	v_cndmask_b32_e32 v48, v48, v49, vcc
	v_rsq_f32_e32 v48, v48
	s_nop 0
	v_mul_f32_e32 v49, 0x45800000, v48
	v_cndmask_b32_e32 v60, v48, v49, vcc
	s_waitcnt vmcnt(0)
	v_mov_b32_e32 v48, v220
	v_mov_b32_e32 v49, v221
	v_mov_b32_e32 v50, v222
	v_mov_b32_e32 v51, v223
	v_pk_mul_f32 v[48:49], v[48:49], v[60:61] op_sel_hi:[1,0]
	s_nop 0
	v_pk_mul_f32 v[80:81], v[80:81], v[48:49]
	v_pk_mul_f32 v[48:49], v[50:51], v[60:61] op_sel_hi:[1,0]
	s_nop 0
	v_pk_mul_f32 v[78:79], v[78:79], v[48:49]
	v_mov_b32_e32 v56, v224
	v_mov_b32_e32 v57, v225
	v_mov_b32_e32 v58, v226
	v_mov_b32_e32 v59, v227
	v_mov_b32_e32 v52, v228
	v_mov_b32_e32 v53, v229
	v_mov_b32_e32 v54, v230
	v_mov_b32_e32 v55, v231
	v_mov_b32_e32 v48, v232
	v_mov_b32_e32 v49, v233
	v_mov_b32_e32 v50, v234
	v_mov_b32_e32 v51, v235
	s_and_saveexec_b64 s[30:31], s[22:23]
	s_cbranch_execz .LBB0_673
	v_readlane_b32 s34, v253, 51
	v_lshlrev_b32_e32 v152, 6, v88
	v_readlane_b32 s35, v253, 52
	ds_bpermute_b32 v98, v61, v80
	ds_bpermute_b32 v99, v61, v81
	v_lshl_add_u64 v[90:91], s[34:35], 0, v[152:153]
	v_lshlrev_b32_e32 v152, 2, v65
	v_lshl_add_u64 v[94:95], v[90:91], 0, v[152:153]
	global_load_dwordx4 v[90:93], v[94:95], off
	s_nop 0
	global_load_dwordx4 v[94:97], v[94:95], off offset:32
	s_waitcnt vmcnt(0) lgkmcnt(0)
	v_pk_mul_f32 v[94:95], v[94:95], v[98:99]
	s_nop 0
	v_cndmask_b32_e64 v95, v95, -v95, s[4:5]
	v_cndmask_b32_e64 v94, v94, -v94, s[4:5]
	v_pk_fma_f32 v[80:81], v[80:81], v[90:91], v[94:95]
	ds_bpermute_b32 v90, v61, v78
	ds_bpermute_b32 v91, v61, v79
	s_waitcnt lgkmcnt(0)
	v_pk_mul_f32 v[90:91], v[96:97], v[90:91]
	s_nop 0
	v_cndmask_b32_e64 v91, v91, -v91, s[4:5]
	v_cndmask_b32_e64 v90, v90, -v90, s[4:5]
	v_pk_fma_f32 v[78:79], v[78:79], v[92:93], v[90:91]

.LBB0_695:
	global_load_dwordx4 v[220:223], v[66:67], off
	global_load_dwordx4 v[224:227], v[66:67], off offset:64
	global_load_dwordx4 v[228:231], v[66:67], off offset:128
	global_load_dwordx4 v[232:235], v[66:67], off offset:192
	v_pk_mul_f32 v[32:33], v[78:79], v[78:79]
	v_pk_mul_f32 v[34:35], v[76:77], v[76:77]
	v_add_f32_e32 v32, v32, v33
	v_add_f32_e32 v32, v34, v32
	v_pk_mul_f32 v[36:37], v[72:73], v[72:73]
	v_add_f32_e32 v32, v35, v32
	v_add_f32_e32 v32, v36, v32
	v_pk_mul_f32 v[38:39], v[70:71], v[70:71]
	v_add_f32_e32 v32, v37, v32
	v_add_f32_e32 v32, v38, v32
	v_pk_mul_f32 v[40:41], v[68:69], v[68:69]
	v_add_f32_e32 v32, v39, v32
	v_add_f32_e32 v32, v40, v32
	v_pk_mul_f32 v[42:43], v[62:63], v[62:63]
	v_add_f32_e32 v32, v41, v32
	v_add_f32_e32 v32, v42, v32
	v_pk_mul_f32 v[74:75], v[46:47], v[46:47]
	v_add_f32_e32 v32, v43, v32
	v_and_b32_e32 v34, 64, v200
	v_add_f32_e32 v32, v74, v32
	v_xor_b32_e32 v33, 16, v200
	v_add_u32_e32 v34, 64, v34
	v_pk_mul_f32 v[80:81], v[44:45], v[44:45]
	v_add_f32_e32 v32, v75, v32
	v_cmp_lt_i32_e32 vcc, v33, v34
	v_add_f32_e32 v32, v80, v32
	v_add_f32_e32 v32, v81, v32
	v_cndmask_b32_e32 v33, v200, v33, vcc
	v_lshlrev_b32_e32 v33, 2, v33
	ds_bpermute_b32 v33, v33, v32
	s_waitcnt lgkmcnt(0)
	v_add_f32_e32 v32, v32, v33
	v_xor_b32_e32 v33, 32, v200
	v_cmp_lt_i32_e32 vcc, v33, v34
	s_nop 1
	v_cndmask_b32_e32 v33, v200, v33, vcc
	v_lshlrev_b32_e32 v53, 2, v33
	ds_bpermute_b32 v33, v53, v32
	s_waitcnt lgkmcnt(0)
	v_add_f32_e32 v32, v32, v33
	v_fmamk_f32 v32, v32, 0x3c800000, v199
	v_cmp_gt_f32_e32 vcc, s73, v32
	v_mul_f32_e32 v33, 0x4b800000, v32
	s_nop 0
	v_cndmask_b32_e32 v32, v32, v33, vcc
	v_rsq_f32_e32 v32, v32
	s_nop 0
	v_mul_f32_e32 v33, 0x45800000, v32
	v_cndmask_b32_e32 v74, v32, v33, vcc
	s_waitcnt vmcnt(0)
	v_mov_b32_e32 v32, v220
	v_mov_b32_e32 v33, v221
	v_mov_b32_e32 v34, v222
	v_mov_b32_e32 v35, v223
	v_pk_mul_f32 v[32:33], v[32:33], v[74:75] op_sel_hi:[1,0]
	s_nop 0
	v_pk_mul_f32 v[78:79], v[78:79], v[32:33]
	v_pk_mul_f32 v[32:33], v[34:35], v[74:75] op_sel_hi:[1,0]
	s_nop 0
	v_pk_mul_f32 v[76:77], v[76:77], v[32:33]
	v_mov_b32_e32 v40, v224
	v_mov_b32_e32 v41, v225
	v_mov_b32_e32 v42, v226
	v_mov_b32_e32 v43, v227
	v_mov_b32_e32 v36, v228
	v_mov_b32_e32 v37, v229
	v_mov_b32_e32 v38, v230
	v_mov_b32_e32 v39, v231
	v_mov_b32_e32 v32, v232
	v_mov_b32_e32 v33, v233
	v_mov_b32_e32 v34, v234
	v_mov_b32_e32 v35, v235
	s_and_saveexec_b64 s[30:31], s[22:23]
	s_cbranch_execz .LBB0_697
	v_readlane_b32 s16, v253, 51
	v_lshlrev_b32_e32 v152, 6, v51
	v_readlane_b32 s17, v253, 52
	ds_bpermute_b32 v92, v53, v78
	ds_bpermute_b32 v93, v53, v79
	v_lshl_add_u64 v[80:81], s[16:17], 0, v[152:153]
	v_lshlrev_b32_e32 v152, 2, v65
	v_lshl_add_u64 v[80:81], v[80:81], 0, v[152:153]
	global_load_dwordx4 v[84:87], v[80:81], off
	global_load_dwordx4 v[88:91], v[80:81], off offset:32
	s_waitcnt vmcnt(0) lgkmcnt(0)
	v_pk_mul_f32 v[80:81], v[88:89], v[92:93]
	s_nop 0
	v_cndmask_b32_e64 v81, v81, -v81, s[4:5]
	v_cndmask_b32_e64 v80, v80, -v80, s[4:5]
	v_pk_fma_f32 v[78:79], v[78:79], v[84:85], v[80:81]
	ds_bpermute_b32 v80, v53, v76
	ds_bpermute_b32 v81, v53, v77
	s_waitcnt lgkmcnt(0)
	v_pk_mul_f32 v[80:81], v[90:91], v[80:81]
	s_nop 0
	v_cndmask_b32_e64 v81, v81, -v81, s[4:5]
	v_cndmask_b32_e64 v80, v80, -v80, s[4:5]
	v_pk_fma_f32 v[76:77], v[76:77], v[86:87], v[80:81]

.LBB0_699:
	global_load_dwordx4 v[220:223], v[66:67], off
	global_load_dwordx4 v[224:227], v[66:67], off offset:64
	global_load_dwordx4 v[228:231], v[66:67], off offset:128
	global_load_dwordx4 v[232:235], v[66:67], off offset:192
	v_pk_mul_f32 v[16:17], v[44:45], v[44:45]
	v_pk_mul_f32 v[18:19], v[42:43], v[42:43]
	v_add_f32_e32 v16, v16, v17
	v_add_f32_e32 v16, v18, v16
	v_pk_mul_f32 v[20:21], v[38:39], v[38:39]
	v_add_f32_e32 v16, v19, v16
	v_add_f32_e32 v16, v20, v16
	v_pk_mul_f32 v[22:23], v[36:37], v[36:37]
	v_add_f32_e32 v16, v21, v16
	v_add_f32_e32 v16, v22, v16
	v_pk_mul_f32 v[24:25], v[34:35], v[34:35]
	v_add_f32_e32 v16, v23, v16
	v_add_f32_e32 v16, v24, v16
	v_pk_mul_f32 v[26:27], v[32:33], v[32:33]
	v_add_f32_e32 v16, v25, v16
	v_add_f32_e32 v16, v26, v16
	v_pk_mul_f32 v[40:41], v[30:31], v[30:31]
	v_add_f32_e32 v16, v27, v16
	v_and_b32_e32 v18, 64, v200
	v_add_f32_e32 v16, v40, v16
	v_xor_b32_e32 v17, 16, v200
	v_add_u32_e32 v18, 64, v18
	v_pk_mul_f32 v[62:63], v[28:29], v[28:29]
	v_add_f32_e32 v16, v41, v16
	v_cmp_lt_i32_e32 vcc, v17, v18
	v_add_f32_e32 v16, v62, v16
	v_add_f32_e32 v16, v63, v16
	v_cndmask_b32_e32 v17, v200, v17, vcc
	v_lshlrev_b32_e32 v17, 2, v17
	ds_bpermute_b32 v17, v17, v16
	s_waitcnt lgkmcnt(0)
	v_add_f32_e32 v16, v16, v17
	v_xor_b32_e32 v17, 32, v200
	v_cmp_lt_i32_e32 vcc, v17, v18
	s_nop 1
	v_cndmask_b32_e32 v17, v200, v17, vcc
	v_lshlrev_b32_e32 v41, 2, v17
	ds_bpermute_b32 v17, v41, v16
	s_waitcnt lgkmcnt(0)
	v_add_f32_e32 v16, v16, v17
	v_fmamk_f32 v16, v16, 0x3c800000, v199
	v_cmp_gt_f32_e32 vcc, s73, v16
	v_mul_f32_e32 v17, 0x4b800000, v16
	s_nop 0
	v_cndmask_b32_e32 v16, v16, v17, vcc
	v_rsq_f32_e32 v16, v16
	s_nop 0
	v_mul_f32_e32 v17, 0x45800000, v16
	v_cndmask_b32_e32 v40, v16, v17, vcc
	s_waitcnt vmcnt(0)
	v_mov_b32_e32 v16, v220
	v_mov_b32_e32 v17, v221
	v_mov_b32_e32 v18, v222
	v_mov_b32_e32 v19, v223
	v_pk_mul_f32 v[16:17], v[16:17], v[40:41] op_sel_hi:[1,0]
	s_nop 0
	v_pk_mul_f32 v[44:45], v[44:45], v[16:17]
	v_pk_mul_f32 v[16:17], v[18:19], v[40:41] op_sel_hi:[1,0]
	s_nop 0
	v_pk_mul_f32 v[42:43], v[42:43], v[16:17]
	v_mov_b32_e32 v24, v224
	v_mov_b32_e32 v25, v225
	v_mov_b32_e32 v26, v226
	v_mov_b32_e32 v27, v227
	v_mov_b32_e32 v20, v228
	v_mov_b32_e32 v21, v229
	v_mov_b32_e32 v22, v230
	v_mov_b32_e32 v23, v231
	v_mov_b32_e32 v16, v232
	v_mov_b32_e32 v17, v233
	v_mov_b32_e32 v18, v234
	v_mov_b32_e32 v19, v235
	s_and_saveexec_b64 s[30:31], s[22:23]
	s_cbranch_execz .LBB0_701
	v_readlane_b32 s16, v253, 51
	v_lshlrev_b32_e32 v152, 6, v47
	v_readlane_b32 s17, v253, 52
	ds_bpermute_b32 v76, v41, v44
	ds_bpermute_b32 v77, v41, v45
	v_lshl_add_u64 v[62:63], s[16:17], 0, v[152:153]
	v_lshlrev_b32_e32 v152, 2, v65
	v_lshl_add_u64 v[62:63], v[62:63], 0, v[152:153]
	global_load_dwordx4 v[68:71], v[62:63], off
	global_load_dwordx4 v[72:75], v[62:63], off offset:32
	s_waitcnt vmcnt(0) lgkmcnt(0)
	v_pk_mul_f32 v[62:63], v[72:73], v[76:77]
	s_nop 0
	v_cndmask_b32_e64 v63, v63, -v63, s[4:5]
	v_cndmask_b32_e64 v62, v62, -v62, s[4:5]
	v_pk_fma_f32 v[44:45], v[44:45], v[68:69], v[62:63]
	ds_bpermute_b32 v62, v41, v42
	ds_bpermute_b32 v63, v41, v43
	s_waitcnt lgkmcnt(0)
	v_pk_mul_f32 v[62:63], v[74:75], v[62:63]
	s_nop 0
	v_cndmask_b32_e64 v63, v63, -v63, s[4:5]
	v_cndmask_b32_e64 v62, v62, -v62, s[4:5]
	v_pk_fma_f32 v[42:43], v[42:43], v[70:71], v[62:63]

.LBB0_703:
	global_load_dwordx4 v[220:223], v[66:67], off
	global_load_dwordx4 v[224:227], v[66:67], off offset:64
	global_load_dwordx4 v[228:231], v[66:67], off offset:128
	global_load_dwordx4 v[232:235], v[66:67], off offset:192
	v_pk_mul_f32 v[2:3], v[26:27], v[26:27]
	v_pk_mul_f32 v[4:5], v[0:1], v[0:1]
	v_add_f32_e32 v2, v2, v3
	v_add_f32_e32 v2, v4, v2
	v_pk_mul_f32 v[6:7], v[24:25], v[24:25]
	v_add_f32_e32 v2, v5, v2
	v_add_f32_e32 v2, v6, v2
	v_pk_mul_f32 v[8:9], v[22:23], v[22:23]
	v_add_f32_e32 v2, v7, v2
	v_add_f32_e32 v2, v8, v2
	v_pk_mul_f32 v[10:11], v[20:21], v[20:21]
	v_add_f32_e32 v2, v9, v2
	v_add_f32_e32 v2, v10, v2
	v_pk_mul_f32 v[14:15], v[18:19], v[18:19]
	v_add_f32_e32 v2, v11, v2
	v_add_f32_e32 v2, v14, v2
	v_pk_mul_f32 v[28:29], v[16:17], v[16:17]
	v_add_f32_e32 v2, v15, v2
	v_and_b32_e32 v4, 64, v200
	v_add_f32_e32 v2, v28, v2
	v_xor_b32_e32 v3, 16, v200
	v_add_u32_e32 v4, 64, v4
	v_pk_mul_f32 v[32:33], v[12:13], v[12:13]
	v_add_f32_e32 v2, v29, v2
	v_cmp_lt_i32_e32 vcc, v3, v4
	v_add_f32_e32 v2, v32, v2
	v_add_f32_e32 v2, v33, v2
	v_cndmask_b32_e32 v3, v200, v3, vcc
	v_lshlrev_b32_e32 v3, 2, v3
	ds_bpermute_b32 v3, v3, v2
	s_waitcnt lgkmcnt(0)
	v_add_f32_e32 v2, v2, v3
	v_xor_b32_e32 v3, 32, v200
	v_cmp_lt_i32_e32 vcc, v3, v4
	s_nop 1
	v_cndmask_b32_e32 v3, v200, v3, vcc
	v_lshlrev_b32_e32 v15, 2, v3
	ds_bpermute_b32 v3, v15, v2
	s_waitcnt lgkmcnt(0)
	v_add_f32_e32 v2, v2, v3
	v_fmamk_f32 v2, v2, 0x3c800000, v199
	v_cmp_gt_f32_e32 vcc, s73, v2
	v_mul_f32_e32 v3, 0x4b800000, v2
	s_nop 0
	v_cndmask_b32_e32 v2, v2, v3, vcc
	v_rsq_f32_e32 v2, v2
	s_nop 0
	v_mul_f32_e32 v3, 0x45800000, v2
	v_cndmask_b32_e32 v14, v2, v3, vcc
	s_waitcnt vmcnt(0)
	v_mov_b32_e32 v2, v220
	v_mov_b32_e32 v3, v221
	v_mov_b32_e32 v4, v222
	v_mov_b32_e32 v5, v223
	v_pk_mul_f32 v[2:3], v[2:3], v[14:15] op_sel_hi:[1,0]
	s_nop 0
	v_pk_mul_f32 v[26:27], v[26:27], v[2:3]
	v_pk_mul_f32 v[2:3], v[4:5], v[14:15] op_sel_hi:[1,0]
	s_nop 0
	v_pk_mul_f32 v[28:29], v[0:1], v[2:3]
	v_mov_b32_e32 v8, v224
	v_mov_b32_e32 v9, v225
	v_mov_b32_e32 v10, v226
	v_mov_b32_e32 v11, v227
	v_mov_b32_e32 v4, v228
	v_mov_b32_e32 v5, v229
	v_mov_b32_e32 v6, v230
	v_mov_b32_e32 v7, v231
	v_mov_b32_e32 v0, v232
	v_mov_b32_e32 v1, v233
	v_mov_b32_e32 v2, v234
	v_mov_b32_e32 v3, v235
	s_and_saveexec_b64 s[24:25], s[22:23]
	s_cbranch_execz .LBB0_705
	v_readlane_b32 s16, v253, 51
	v_lshlrev_b32_e32 v152, 6, v31
	v_readlane_b32 s17, v253, 52
	ds_bpermute_b32 v40, v15, v26
	ds_bpermute_b32 v41, v15, v27
	v_lshl_add_u64 v[32:33], s[16:17], 0, v[152:153]
	v_lshlrev_b32_e32 v152, 2, v65
	v_lshl_add_u64 v[36:37], v[32:33], 0, v[152:153]
	global_load_dwordx4 v[32:35], v[36:37], off
	s_nop 0
	global_load_dwordx4 v[36:39], v[36:37], off offset:32
	s_waitcnt vmcnt(0) lgkmcnt(0)
	v_pk_mul_f32 v[36:37], v[36:37], v[40:41]
	s_nop 0
	v_cndmask_b32_e64 v37, v37, -v37, s[4:5]
	v_cndmask_b32_e64 v36, v36, -v36, s[4:5]
	v_pk_fma_f32 v[26:27], v[26:27], v[32:33], v[36:37]
	ds_bpermute_b32 v32, v15, v28
	ds_bpermute_b32 v33, v15, v29
	s_waitcnt lgkmcnt(0)
	v_pk_mul_f32 v[32:33], v[38:39], v[32:33]
	s_nop 0
	v_cndmask_b32_e64 v33, v33, -v33, s[4:5]
	v_cndmask_b32_e64 v32, v32, -v32, s[4:5]
	v_pk_fma_f32 v[28:29], v[28:29], v[34:35], v[32:33]
